# w_down also in LDS-image order (remapped conversion), down-GEMM stages both operands linearly
# baseline (speedup 1.0000x reference)
.LBB0_1776:
	s_add_i32 s13, s12, s10
	s_cmpk_gt_i32 s13, 0x5aff
	s_cbranch_scc1 .LBB0_1775
	s_cmpk_gt_i32 s13, 0x12ff
	s_mov_b64 s[10:11], -1
	s_cbranch_scc0 .LBB0_1787
	s_cmpk_gt_u32 s13, 0x1aff
	s_cbranch_scc0 .LBB0_1784
	s_cmpk_gt_u32 s13, 0x3aff
	s_cbranch_scc0 .LBB0_1781
	s_and_b32 s10, s13, 0x7fffffc0
	s_addk_i32 s10, 0xc500
	s_lshl_b32 s11, s13, 5
	s_and_b32 s14, s11, 0x7e0
	v_add_u32_e32 v24, s10, v1
	s_lshl_b32 s90, s14, 2
	v_ashrrev_i32_e32 v25, 31, v24
	v_lshl_add_u64 v[32:33], v[6:7], 0, s[90:91]
	v_lshlrev_b64 v[24:25], 13, v[24:25]
	v_lshl_add_u64 v[24:25], v[32:33], 0, v[24:25]
	v_add_co_u32_e32 v32, vcc, 0x4000, v24
	global_load_dword v5, v[24:25], off nt
	s_nop 0
	v_addc_co_u32_e32 v33, vcc, 0, v25, vcc
	global_load_dword v11, v[32:33], off nt
	v_add_co_u32_e32 v32, vcc, 0x8000, v24
	s_mov_b32 s11, 0xc000
	s_nop 0
	v_addc_co_u32_e32 v33, vcc, 0, v25, vcc
	global_load_dword v18, v[32:33], off nt
	v_add_co_u32_e32 v32, vcc, s11, v24
	s_mov_b32 s11, 0x10000
	s_nop 0
	v_addc_co_u32_e32 v33, vcc, 0, v25, vcc
	global_load_dword v31, v[32:33], off nt
	v_add_co_u32_e32 v32, vcc, s11, v24
	s_mov_b32 s11, 0x14000
	s_nop 0
	v_addc_co_u32_e32 v33, vcc, 0, v25, vcc
	global_load_dword v34, v[32:33], off nt
	v_add_co_u32_e32 v32, vcc, s11, v24
	s_mov_b32 s11, 0x18000
	s_nop 0
	v_addc_co_u32_e32 v33, vcc, 0, v25, vcc
	global_load_dword v35, v[32:33], off nt
	v_add_co_u32_e32 v32, vcc, s11, v24
	s_mov_b32 s11, 0x1c000
	s_nop 0
	v_addc_co_u32_e32 v33, vcc, 0, v25, vcc
	global_load_dword v36, v[32:33], off nt
	v_add_co_u32_e32 v32, vcc, s11, v24
	s_mov_b32 s11, 0x20000
	s_nop 0
	v_addc_co_u32_e32 v33, vcc, 0, v25, vcc
	global_load_dword v37, v[32:33], off nt
	v_add_co_u32_e32 v32, vcc, s11, v24
	s_mov_b32 s11, 0x58000
	s_nop 0
	v_addc_co_u32_e32 v33, vcc, 0, v25, vcc
	global_load_dword v38, v[32:33], off nt
	v_add_co_u32_e32 v32, vcc, s19, v24
	s_lshr_b32 s90, s10, 6
	s_nop 0
	v_addc_co_u32_e32 v33, vcc, 0, v25, vcc
	global_load_dword v39, v[32:33], off nt
	v_add_co_u32_e32 v32, vcc, s20, v24
	s_nop 1
	v_addc_co_u32_e32 v33, vcc, 0, v25, vcc
	global_load_dword v40, v[32:33], off nt
	v_add_co_u32_e32 v32, vcc, s21, v24
	s_nop 1
	v_addc_co_u32_e32 v33, vcc, 0, v25, vcc
	global_load_dword v41, v[32:33], off nt
	v_add_co_u32_e32 v32, vcc, s22, v24
	s_nop 1
	v_addc_co_u32_e32 v33, vcc, 0, v25, vcc
	global_load_dword v42, v[32:33], off nt
	v_add_co_u32_e32 v32, vcc, s23, v24
	s_nop 1
	v_addc_co_u32_e32 v33, vcc, 0, v25, vcc
	global_load_dword v43, v[32:33], off nt
	v_add_co_u32_e32 v32, vcc, s24, v24
	s_nop 1
	v_addc_co_u32_e32 v33, vcc, 0, v25, vcc
	global_load_dword v44, v[32:33], off nt
	v_add_co_u32_e32 v32, vcc, s25, v24
	s_nop 1
	v_addc_co_u32_e32 v33, vcc, 0, v25, vcc
	global_load_dword v45, v[32:33], off nt
	v_add_co_u32_e32 v32, vcc, s26, v24
	s_nop 1
	v_addc_co_u32_e32 v33, vcc, 0, v25, vcc
	global_load_dword v46, v[32:33], off nt
	v_add_co_u32_e32 v32, vcc, s27, v24
	s_nop 1
	v_addc_co_u32_e32 v33, vcc, 0, v25, vcc
	global_load_dword v47, v[32:33], off nt
	v_add_co_u32_e32 v32, vcc, s43, v24
	s_nop 1
	v_addc_co_u32_e32 v33, vcc, 0, v25, vcc
	global_load_dword v48, v[32:33], off nt
	v_add_co_u32_e32 v32, vcc, s44, v24
	s_nop 1
	v_addc_co_u32_e32 v33, vcc, 0, v25, vcc
	global_load_dword v49, v[32:33], off nt
	v_add_co_u32_e32 v32, vcc, s45, v24
	s_nop 1
	v_addc_co_u32_e32 v33, vcc, 0, v25, vcc
	global_load_dword v50, v[32:33], off nt
	v_add_co_u32_e32 v32, vcc, s46, v24
	s_nop 1
	v_addc_co_u32_e32 v33, vcc, 0, v25, vcc
	global_load_dword v51, v[32:33], off nt
	v_add_co_u32_e32 v32, vcc, s11, v24
	s_mov_b32 s11, 0x5c000
	s_nop 0
	v_addc_co_u32_e32 v33, vcc, 0, v25, vcc
	global_load_dword v52, v[32:33], off nt
	v_add_co_u32_e32 v32, vcc, s11, v24
	s_mov_b32 s11, 0x60000
	s_nop 0
	v_addc_co_u32_e32 v33, vcc, 0, v25, vcc
	global_load_dword v53, v[32:33], off nt
	v_add_co_u32_e32 v32, vcc, s11, v24
	s_mov_b32 s11, 0x64000
	s_nop 0
	v_addc_co_u32_e32 v33, vcc, 0, v25, vcc
	global_load_dword v54, v[32:33], off nt
	v_add_co_u32_e32 v32, vcc, s11, v24
	s_mov_b32 s11, 0x68000
	s_nop 0
	v_addc_co_u32_e32 v33, vcc, 0, v25, vcc
	global_load_dword v55, v[32:33], off nt
	v_add_co_u32_e32 v32, vcc, s11, v24
	s_mov_b32 s11, 0x6c000
	s_nop 0
	v_addc_co_u32_e32 v33, vcc, 0, v25, vcc
	global_load_dword v56, v[32:33], off nt
	v_add_co_u32_e32 v32, vcc, s11, v24
	s_mov_b32 s11, 0x70000
	s_nop 0
	v_addc_co_u32_e32 v33, vcc, 0, v25, vcc
	global_load_dword v57, v[32:33], off nt
	v_add_co_u32_e32 v32, vcc, s11, v24
	s_mov_b32 s11, 0x74000
	s_nop 0
	v_addc_co_u32_e32 v33, vcc, 0, v25, vcc
	global_load_dword v58, v[32:33], off nt
	v_add_co_u32_e32 v32, vcc, s11, v24
	s_mov_b32 s11, 0x78000
	s_nop 0
	v_addc_co_u32_e32 v33, vcc, 0, v25, vcc
	global_load_dword v59, v[32:33], off nt
	v_add_co_u32_e32 v32, vcc, s11, v24
	s_mov_b32 s11, 0x7c000
	s_nop 0
	v_addc_co_u32_e32 v33, vcc, 0, v25, vcc
	v_add_co_u32_e32 v24, vcc, s11, v24
	global_load_dword v32, v[32:33], off nt
	s_nop 0
	v_addc_co_u32_e32 v25, vcc, 0, v25, vcc
	global_load_dword v24, v[24:25], off nt
	s_waitcnt vmcnt(0)
	ds_write2_b32 v3, v5, v11 offset1:66
	ds_write2_b32 v3, v18, v31 offset0:132 offset1:198
	v_add_u32_e32 v5, 0x400, v3
	ds_write2_b32 v5, v34, v35 offset0:8 offset1:74
	ds_write2_b32 v5, v36, v37 offset0:140 offset1:206
	v_add_u32_e32 v5, 0x800, v3
	ds_write2_b32 v5, v38, v39 offset0:16 offset1:82
	ds_write2_b32 v5, v40, v41 offset0:148 offset1:214
	v_add_u32_e32 v5, 0xc00, v3
	ds_write2_b32 v5, v42, v43 offset0:24 offset1:90
	ds_write2_b32 v5, v44, v45 offset0:156 offset1:222
	v_add_u32_e32 v5, 0x1000, v3
	ds_write2_b32 v5, v46, v47 offset0:32 offset1:98
	ds_write2_b32 v5, v48, v49 offset0:164 offset1:230
	v_add_u32_e32 v5, 0x1400, v3
	ds_write2_b32 v5, v50, v51 offset0:40 offset1:106
	ds_write2_b32 v5, v52, v53 offset0:172 offset1:238
	v_add_u32_e32 v5, 0x1800, v3
	ds_write2_b32 v5, v54, v55 offset0:48 offset1:114
	ds_write2_b32 v5, v56, v57 offset0:180 offset1:246
	v_add_u32_e32 v5, 0x1c00, v3
	ds_write2_b32 v5, v58, v59 offset0:56 offset1:122
	ds_write2_b32 v5, v32, v24 offset0:188 offset1:254
	s_waitcnt lgkmcnt(0)
	v_and_b32_e32 v70, 3, v146
	v_mul_u32_u24_e32 v70, 0x420, v70
	v_lshrrev_b32_e32 v71, 4, v146
	v_lshl_add_u32 v70, v71, 5, v70
	v_bfe_u32 v71, v146, 2, 2
	v_lshl_add_u32 v70, v71, 2, v70
	s_lshl_b32 s100, s42, 14
	v_add_u32_e32 v70, s100, v70
	v_add_u32_e32 v71, 0x1080, v70
	ds_read2_b32 v[24:25], v70 offset0:33 offset1:37
	ds_read2_b32 v[36:37], v70 offset1:4
	ds_read2_b32 v[38:39], v70 offset0:66 offset1:70
	ds_read2_b32 v[40:41], v70 offset0:99 offset1:103
	ds_read2_b32 v[42:43], v70 offset0:132 offset1:136
	ds_read2_b32 v[44:45], v70 offset0:165 offset1:169
	ds_read2_b32 v[46:47], v70 offset0:198 offset1:202
	ds_read2_b32 v[48:49], v70 offset0:231 offset1:235
	s_waitcnt lgkmcnt(7)
	v_bfe_u32 v11, v24, 16, 1
	s_waitcnt lgkmcnt(6)
	v_bfe_u32 v5, v36, 16, 1
	v_add3_u32 v5, v36, v5, s79
	v_lshrrev_b32_e32 v5, 16, v5
	v_add3_u32 v11, v24, v11, s79
	v_and_or_b32 v32, v11, s80, v5
	s_waitcnt lgkmcnt(5)
	v_bfe_u32 v5, v38, 16, 1
	v_add3_u32 v5, v38, v5, s79
	s_waitcnt lgkmcnt(4)
	v_bfe_u32 v11, v40, 16, 1
	v_lshrrev_b32_e32 v5, 16, v5
	v_add3_u32 v11, v40, v11, s79
	v_and_or_b32 v33, v11, s80, v5
	s_waitcnt lgkmcnt(3)
	v_bfe_u32 v5, v42, 16, 1
	v_add3_u32 v5, v42, v5, s79
	s_waitcnt lgkmcnt(2)
	v_bfe_u32 v11, v44, 16, 1
	v_lshrrev_b32_e32 v5, 16, v5
	v_add3_u32 v11, v44, v11, s79
	v_and_or_b32 v34, v11, s80, v5
	s_waitcnt lgkmcnt(1)
	v_bfe_u32 v5, v46, 16, 1
	v_add3_u32 v5, v46, v5, s79
	s_waitcnt lgkmcnt(0)
	v_bfe_u32 v11, v48, 16, 1
	v_lshrrev_b32_e32 v5, 16, v5
	v_add3_u32 v11, v48, v11, s79
	v_and_or_b32 v35, v11, s80, v5
	v_add_u32_e32 v5, s14, v26
	v_ashrrev_i32_e32 v50, 8, v5
	v_ashrrev_i32_e32 v51, 31, v50
	v_lshlrev_b64 v[50:51], 22, v[50:51]
	s_lshl_b64 s[10:11], s[90:91], 15
	s_lshr_b32 s100, s14, 8
	s_lshl_b32 s100, s100, 22
	s_bfe_u32 s101, s14, 0x10007
	s_lshl_b32 s101, s101, 14
	s_add_i32 s100, s100, s101
	s_bfe_u32 s101, s14, 0x20005
	s_lshl_b32 s101, s101, 12
	s_add_i32 s100, s100, s101
	v_lshrrev_b32_e32 v62, 5, v146
	v_lshlrev_b32_e32 v62, 5, v62
	v_lshlrev_b32_e32 v64, 4, v146
	v_xor_b32_e32 v62, v62, v64
	v_add_u32_e32 v62, s100, v62
	v_mov_b32_e32 v63, v19
	v_lshl_add_u64 v[68:69], s[0:1], 0, v[62:63]
	v_lshl_add_u64 v[68:69], v[68:69], 0, s[10:11]
	v_lshl_add_u64 v[50:51], s[0:1], 0, v[50:51]
	v_lshlrev_b32_e32 v5, 7, v5
	v_lshl_add_u64 v[50:51], v[50:51], 0, s[10:11]
	v_and_b32_e32 v18, 0x7f80, v5
	v_bfe_u32 v5, v37, 16, 1
	v_lshl_add_u64 v[50:51], v[50:51], 0, v[18:19]
	v_mov_b32_e32 v11, v19
	v_add3_u32 v5, v37, v5, s79
	v_bfe_u32 v18, v25, 16, 1
	v_lshl_add_u64 v[50:51], v[50:51], 0, v[10:11]
	v_lshrrev_b32_e32 v5, 16, v5
	v_add3_u32 v18, v25, v18, s79
	global_store_dwordx4 v[68:69], v[32:35], off nt
	s_nop 1
	v_and_or_b32 v32, v18, s80, v5
	v_bfe_u32 v5, v39, 16, 1
	v_add3_u32 v5, v39, v5, s79
	v_bfe_u32 v18, v41, 16, 1
	v_lshrrev_b32_e32 v5, 16, v5
	v_add3_u32 v18, v41, v18, s79
	v_and_or_b32 v33, v18, s80, v5
	v_bfe_u32 v5, v43, 16, 1
	v_add3_u32 v5, v43, v5, s79
	v_bfe_u32 v18, v45, 16, 1
	v_lshrrev_b32_e32 v5, 16, v5
	v_add3_u32 v18, v45, v18, s79
	v_and_or_b32 v34, v18, s80, v5
	v_bfe_u32 v5, v47, 16, 1
	v_add3_u32 v5, v47, v5, s79
	v_bfe_u32 v18, v49, 16, 1
	v_lshrrev_b32_e32 v5, 16, v5
	v_add3_u32 v18, v49, v18, s79
	v_and_or_b32 v35, v18, s80, v5
	v_add_u32_e32 v5, s14, v28
	v_ashrrev_i32_e32 v24, 8, v5
	v_ashrrev_i32_e32 v25, 31, v24
	v_lshlrev_b64 v[24:25], 22, v[24:25]
	v_lshl_add_u64 v[24:25], s[0:1], 0, v[24:25]
	v_lshlrev_b32_e32 v5, 7, v5
	v_lshl_add_u64 v[24:25], v[24:25], 0, s[10:11]
	v_and_b32_e32 v18, 0x7f80, v5
	v_lshl_add_u64 v[24:25], v[24:25], 0, v[18:19]
	v_lshl_add_u64 v[24:25], v[24:25], 0, v[10:11]
	global_store_dwordx4 v[68:69], v[32:35], off offset:2048 nt
	ds_read2_b32 v[24:25], v71 offset1:4
	ds_read2_b32 v[36:37], v71 offset0:33 offset1:37
	ds_read2_b32 v[38:39], v71 offset0:66 offset1:70
	ds_read2_b32 v[40:41], v71 offset0:99 offset1:103
	ds_read2_b32 v[42:43], v71 offset0:132 offset1:136
	ds_read2_b32 v[44:45], v71 offset0:165 offset1:169
	ds_read2_b32 v[46:47], v71 offset0:198 offset1:202
	ds_read2_b32 v[48:49], v71 offset0:231 offset1:235
	s_waitcnt lgkmcnt(7)
	v_bfe_u32 v5, v24, 16, 1
	v_add3_u32 v5, v24, v5, s79
	s_waitcnt lgkmcnt(6)
	v_bfe_u32 v18, v36, 16, 1
	v_lshrrev_b32_e32 v5, 16, v5
	v_add3_u32 v18, v36, v18, s79
	v_and_or_b32 v32, v18, s80, v5
	s_waitcnt lgkmcnt(5)
	v_bfe_u32 v5, v38, 16, 1
	v_add3_u32 v5, v38, v5, s79
	s_waitcnt lgkmcnt(4)
	v_bfe_u32 v18, v40, 16, 1
	v_lshrrev_b32_e32 v5, 16, v5
	v_add3_u32 v18, v40, v18, s79
	v_and_or_b32 v33, v18, s80, v5
	s_waitcnt lgkmcnt(3)
	v_bfe_u32 v5, v42, 16, 1
	v_add3_u32 v5, v42, v5, s79
	s_waitcnt lgkmcnt(2)
	v_bfe_u32 v18, v44, 16, 1
	v_lshrrev_b32_e32 v5, 16, v5
	v_add3_u32 v18, v44, v18, s79
	v_and_or_b32 v34, v18, s80, v5
	s_waitcnt lgkmcnt(1)
	v_bfe_u32 v5, v46, 16, 1
	v_add3_u32 v5, v46, v5, s79
	s_waitcnt lgkmcnt(0)
	v_bfe_u32 v18, v48, 16, 1
	v_lshrrev_b32_e32 v5, 16, v5
	v_add3_u32 v18, v48, v18, s79
	v_and_or_b32 v35, v18, s80, v5
	v_add_u32_e32 v5, s14, v29
	v_ashrrev_i32_e32 v50, 8, v5
	v_ashrrev_i32_e32 v51, 31, v50
	v_lshlrev_b64 v[50:51], 22, v[50:51]
	v_lshl_add_u64 v[50:51], s[0:1], 0, v[50:51]
	v_lshlrev_b32_e32 v5, 7, v5
	v_lshl_add_u64 v[50:51], v[50:51], 0, s[10:11]
	v_and_b32_e32 v18, 0x7f80, v5
	v_bfe_u32 v5, v25, 16, 1
	v_lshl_add_u64 v[50:51], v[50:51], 0, v[18:19]
	v_add3_u32 v5, v25, v5, s79
	v_bfe_u32 v18, v37, 16, 1
	v_lshl_add_u64 v[50:51], v[50:51], 0, v[10:11]
	v_lshrrev_b32_e32 v5, 16, v5
	v_add3_u32 v18, v37, v18, s79
	global_store_dwordx4 v[68:69], v[32:35], off offset:1024 nt
	s_nop 1
	v_and_or_b32 v32, v18, s80, v5
	v_bfe_u32 v5, v39, 16, 1
	v_add3_u32 v5, v39, v5, s79
	v_bfe_u32 v18, v41, 16, 1
	v_lshrrev_b32_e32 v5, 16, v5
	v_add3_u32 v18, v41, v18, s79
	v_and_or_b32 v33, v18, s80, v5
	v_bfe_u32 v5, v43, 16, 1
	v_add3_u32 v5, v43, v5, s79
	v_bfe_u32 v18, v45, 16, 1
	v_lshrrev_b32_e32 v5, 16, v5
	v_add3_u32 v18, v45, v18, s79
	v_and_or_b32 v34, v18, s80, v5
	v_bfe_u32 v5, v47, 16, 1
	v_add3_u32 v5, v47, v5, s79
	v_bfe_u32 v18, v49, 16, 1
	v_lshrrev_b32_e32 v5, 16, v5
	v_add3_u32 v18, v49, v18, s79
	v_and_or_b32 v35, v18, s80, v5
	v_add_u32_e32 v5, s14, v30
	v_ashrrev_i32_e32 v24, 8, v5
	v_ashrrev_i32_e32 v25, 31, v24
	v_lshlrev_b64 v[24:25], 22, v[24:25]
	v_lshl_add_u64 v[24:25], s[0:1], 0, v[24:25]
	v_lshlrev_b32_e32 v5, 7, v5
	v_lshl_add_u64 v[24:25], v[24:25], 0, s[10:11]
	v_and_b32_e32 v18, 0x7f80, v5
	v_lshl_add_u64 v[24:25], v[24:25], 0, v[18:19]
	v_lshl_add_u64 v[24:25], v[24:25], 0, v[10:11]
	global_store_dwordx4 v[68:69], v[32:35], off offset:3072 nt
	s_waitcnt lgkmcnt(0)
	s_mov_b64 s[10:11], 0

.LBB0_1842:
	v_bfe_i32 v4, v2, 27, 1
	v_lshlrev_b32_e32 v1, 4, v2
	v_lshrrev_b32_e32 v4, 22, v4
	v_ashrrev_i32_e32 v3, 31, v2
	v_add_u32_e32 v4, v1, v4
	v_lshrrev_b32_e32 v3, 26, v3
	v_and_b32_e32 v4, 0xfffffc00, v4
	v_add_u32_e32 v3, v2, v3
	v_sub_u32_e32 v4, v1, v4
	v_ashrrev_i32_e32 v3, 6, v3
	v_lshrrev_b32_e32 v5, 4, v4
	v_bitop3_b32 v5, v5, v4, 32 bitop3:0x6c
	v_lshlrev_b32_e32 v4, 3, v3
	s_waitcnt lgkmcnt(4)
	v_and_b32_e32 v6, -16, v4
	v_ashrrev_i32_e32 v4, 31, v5
	v_lshrrev_b32_e32 v4, 26, v4
	v_add_u32_e32 v7, v5, v4
	s_add_u32 s42, s8, 0x37300000
	s_mov_b32 s89, s91
	v_ashrrev_i32_e32 v4, 6, v7
	v_and_b32_e32 v7, 0xc0, v7
	s_addc_u32 s43, s9, 0
	s_lshl_b64 s[8:9], s[88:89], 25
	v_sub_u32_e32 v5, v5, v7
	s_add_u32 s6, s6, s8
	s_waitcnt lgkmcnt(2)
	v_lshlrev_b32_e32 v8, 5, v3
	v_ashrrev_i16_sdwa v5, v210, sext(v5) dst_sel:DWORD dst_unused:UNUSED_PAD src0_sel:DWORD src1_sel:BYTE_0
	s_addc_u32 s7, s7, s9
	v_and_b32_e32 v8, 32, v8
	v_bfe_i32 v5, v5, 0, 16
	s_add_u32 s44, s6, 0x3f900000
	v_add_u32_e32 v6, v4, v6
	v_and_b32_e32 v10, 3, v4
	s_mov_b32 s6, 0x1ffffe0
	v_add_lshl_u32 v8, v8, v5, 1
	v_add_u32_e32 v1, 0x2000, v1
	v_lshlrev_b32_e32 v7, 1, v6
	v_lshrrev_b32_e32 v9, 2, v6
	v_and_or_b32 v10, v6, s6, v10
	v_lshlrev_b32_e32 v148, 4, v2
	v_ashrrev_i32_e32 v6, 31, v1
	v_lshrrev_b32_e32 v6, 22, v6
	v_and_b32_e32 v7, 24, v7
	v_and_b32_e32 v9, 4, v9
	v_add_u32_e32 v6, v1, v6
	v_or3_b32 v7, v10, v9, v7
	v_ashrrev_i32_e32 v6, 10, v6
	v_lshlrev_b32_e32 v18, 4, v2
	v_mul_i32_i24_e32 v7, 0x400, v6
	v_sub_u32_e32 v1, v1, v7
	v_lshrrev_b32_e32 v7, 4, v1
	v_bitop3_b32 v1, v7, v1, 32 bitop3:0x6c
	v_lshlrev_b32_e32 v7, 3, v6
	v_and_b32_e32 v8, -16, v7
	v_ashrrev_i32_e32 v7, 31, v1
	v_lshrrev_b32_e32 v7, 26, v7
	v_add_u32_e32 v9, v1, v7
	v_ashrrev_i32_e32 v7, 6, v9
	s_addc_u32 s45, s7, 0
	v_add_u32_e32 v10, v7, v8
	s_waitcnt lgkmcnt(0)
	v_and_b32_e32 v12, 3, v7
	s_ashr_i32 s14, s12, 6
	s_ashr_i32 s21, s20, 31
	s_ashr_i32 s23, s22, 31
	s_ashr_i32 s13, s12, 8
	v_and_or_b32 v12, v10, s6, v12
	s_lshl_b32 s46, s14, 10
	s_lshl_b64 s[6:7], s[20:21], 22
	s_lshl_b32 s10, s58, 9
	s_lshl_b64 s[8:9], s[22:23], 22
	s_add_u32 s8, s44, s8
	v_lshlrev_b32_e32 v8, 5, v6
	s_addc_u32 s9, s45, s9
	v_and_b32_e32 v11, 32, v8
	v_and_b32_e32 v8, 0xc0, v9
	s_add_u32 s24, s8, s10
	v_sub_u32_e32 v1, v1, v8
	s_addc_u32 s25, s9, 0
	s_add_i32 s21, s46, 0
	v_ashrrev_i16_sdwa v1, v210, sext(v1) dst_sel:DWORD dst_unused:UNUSED_PAD src0_sel:DWORD src1_sel:BYTE_0
	s_add_i32 m0, s21, 0x10000
	v_bfe_i32 v8, v1, 0, 16
	v_lshlrev_b32_e32 v1, 1, v10
	v_lshrrev_b32_e32 v9, 2, v10
	global_load_lds_dwordx4 v18, s[24:25]
	s_add_i32 m0, s21, 0x12000
	v_and_b32_e32 v1, 24, v1
	v_and_b32_e32 v9, 4, v9
	s_add_u32 s8, s42, s6
	v_or3_b32 v1, v12, v9, v1
	v_add_lshl_u32 v9, v11, v8, 1
	s_addc_u32 s9, s43, s7
	v_add_u32_e32 v152, 0x2000, v18
	s_add_u32 s6, s24, 0x4000
	global_load_lds_dwordx4 v152, s[24:25]
	s_addc_u32 s7, s25, 0
	s_add_i32 m0, s21, 0x14000
	v_add_u32_e32 v150, 0x2000, v148
	global_load_lds_dwordx4 v18, s[6:7]
	s_add_i32 m0, s21, 0x16000
	s_add_u32 s26, s8, s10
	s_addc_u32 s27, s9, 0
	s_add_i32 s47, s21, 0x2000
	global_load_lds_dwordx4 v152, s[6:7]
	s_mov_b32 m0, s21
	s_add_u32 s6, s26, 0x4000
	global_load_lds_dwordx4 v148, s[26:27]
	s_mov_b32 m0, s47
	s_addc_u32 s7, s27, 0
	s_add_i32 s48, s21, 0x4000
	global_load_lds_dwordx4 v150, s[26:27]
	s_mov_b32 m0, s48
	s_add_i32 s49, s21, 0x6000
	global_load_lds_dwordx4 v148, s[6:7]
	s_mov_b32 m0, s49
	s_cmp_eq_u32 s13, 1
	global_load_lds_dwordx4 v150, s[6:7]
	s_cselect_b64 s[6:7], -1, 0
	s_cmp_lg_u32 s13, 1
	s_cbranch_scc1 .LBB0_1844
	s_barrier
